# wave 0 issues its x-tile preload inside the panel barrier (after its arrival) instead of at the start of the attention-combine phase
# baseline (speedup 1.0000x reference)
.Lg_rest:
	s_or_b64 exec, exec, s[64:65]
.Lg_skip:
	v_ashrrev_i32_e32 v3, 31, v2
	v_lshl_add_u64 v[4:5], v[2:3], 2, s[4:5]
	s_mov_b64 s[8:9], 0x2b00000
	v_lshl_add_u64 v[6:7], v[4:5], 0, s[8:9]
	v_add_co_u32_e32 v4, vcc, 0x2b00000, v4
	v_mbcnt_lo_u32_b32 v1, -1, 0
	s_nop 0
	v_addc_co_u32_e32 v5, vcc, 0, v5, vcc
	flat_load_dword v3, v[4:5]
	flat_load_dword v8, v[6:7] offset:256
	flat_load_dword v9, v[6:7] offset:512
	flat_load_dword v10, v[6:7] offset:768
	v_mbcnt_hi_u32_b32 v4, -1, v1
	v_and_b32_e32 v1, 64, v4
	v_xor_b32_e32 v5, 1, v4
	v_add_u32_e32 v14, 64, v1
	v_cmp_lt_i32_e32 vcc, v5, v14
	v_xor_b32_e32 v6, 2, v4
	v_xor_b32_e32 v7, 4, v4
	v_cndmask_b32_e32 v1, v4, v5, vcc
	v_lshlrev_b32_e32 v1, 2, v1
	v_cmp_lt_i32_e32 vcc, v6, v14
	v_xor_b32_e32 v11, 8, v4
	v_xor_b32_e32 v12, 16, v4
	v_cndmask_b32_e32 v6, v4, v6, vcc
	v_lshlrev_b32_e32 v28, 2, v6
	v_cmp_lt_i32_e32 vcc, v7, v14
	v_xor_b32_e32 v13, 32, v4
	s_and_b32 s8, s2, 7
	s_lshl_b32 s8, s8, 2
	s_bfe_u32 s9, s2, 0x20003
	s_add_i32 s8, s8, s9
	s_lshl_b32 s8, s8, 8
	s_lshr_b32 s9, s2, 5
	s_lshl_b32 s9, s9, 5
	s_add_i32 s8, s8, s9
	s_add_i32 s60, s8, 32
	v_cndmask_b32_e32 v7, v4, v7, vcc
	v_lshlrev_b32_e32 v29, 2, v7
	v_cmp_lt_i32_e32 vcc, v11, v14
	s_add_i32 s8, s28, s8
	s_cmpk_lt_i32 s8, 0x2000
	s_waitcnt vmcnt(0) lgkmcnt(0)
	v_mul_f32_e32 v5, v3, v8
	ds_bpermute_b32 v5, v1, v5
	v_mul_f32_e32 v15, v9, v10
	ds_bpermute_b32 v15, v1, v15
	s_waitcnt lgkmcnt(1)
	v_fmac_f32_e32 v5, v3, v8
	ds_bpermute_b32 v3, v28, v5
	s_waitcnt lgkmcnt(1)
	v_fmac_f32_e32 v15, v9, v10
	ds_bpermute_b32 v6, v28, v15
	v_cndmask_b32_e32 v8, v4, v11, vcc
	v_lshlrev_b32_e32 v8, 2, v8
	s_waitcnt lgkmcnt(1)
	v_add_f32_e32 v3, v5, v3
	v_cmp_lt_i32_e32 vcc, v12, v14
	s_waitcnt lgkmcnt(0)
	v_add_f32_e32 v5, v15, v6
	ds_bpermute_b32 v6, v29, v3
	ds_bpermute_b32 v7, v29, v5
	s_waitcnt lgkmcnt(1)
	v_add_f32_e32 v3, v3, v6
	s_waitcnt lgkmcnt(0)
	v_add_f32_e32 v5, v5, v7
	ds_bpermute_b32 v6, v8, v3
	ds_bpermute_b32 v7, v8, v5
	v_cndmask_b32_e32 v8, v4, v12, vcc
	v_lshlrev_b32_e32 v8, 2, v8
	v_cmp_lt_i32_e32 vcc, v13, v14
	s_waitcnt lgkmcnt(1)
	v_add_f32_e32 v3, v3, v6
	s_waitcnt lgkmcnt(0)
	v_add_f32_e32 v6, v5, v7
	ds_bpermute_b32 v5, v8, v3
	ds_bpermute_b32 v7, v8, v6
	v_cndmask_b32_e32 v4, v4, v13, vcc
	v_lshlrev_b32_e32 v4, 2, v4
	s_waitcnt lgkmcnt(1)
	v_add_f32_e32 v5, v3, v5
	s_waitcnt lgkmcnt(0)
	v_add_f32_e32 v3, v6, v7
	ds_bpermute_b32 v6, v4, v5
	ds_bpermute_b32 v4, v4, v3
	s_cbranch_scc0 .LBB0_566
	v_lshlrev_b32_e32 v7, 6, v2
	v_and_b32_e32 v8, 0x1c0, v7
	v_mov_b32_e32 v9, 0
	v_lshl_add_u64 v[8:9], s[4:5], 0, v[8:9]
	s_mov_b64 s[10:11], 0x2b00400
	v_lshl_add_u64 v[18:19], v[8:9], 0, s[10:11]
	v_add_co_u32_e32 v8, vcc, 0x2b00000, v8
	flat_load_dwordx4 v[10:13], v[18:19] offset:16
	flat_load_dwordx4 v[14:17], v[18:19] offset:32
	v_addc_co_u32_e32 v9, vcc, 0, v9, vcc
	flat_load_dwordx4 v[20:23], v[8:9] offset:1024
	flat_load_dwordx4 v[24:27], v[18:19] offset:48
	s_waitcnt lgkmcnt(0)
	v_add_f32_e32 v6, v5, v6
	v_lshlrev_b32_e32 v8, 4, v2
	s_mov_b32 s11, 0x3fb8aa3b
	v_add_f32_e32 v3, v3, v4
	v_mul_f32_e32 v18, 0x3fb8aa3b, v6
	v_mul_f32_e32 v19, 0x3fb8aa3b, v3
	v_ashrrev_i32_e32 v9, 31, v8
	v_fma_f32 v30, v6, s11, -v18
	v_rndne_f32_e32 v31, v18
	v_fma_f32 v32, v3, s11, -v19
	v_rndne_f32_e32 v33, v19
	v_lshlrev_b64 v[4:5], 1, v[8:9]
	v_fmac_f32_e32 v30, 0x32a5705f, v6
	v_sub_f32_e32 v8, v18, v31
	v_fmac_f32_e32 v32, 0x32a5705f, v3
	v_sub_f32_e32 v18, v19, v33
	v_add_f32_e32 v8, v8, v30
	v_cvt_i32_f32_e32 v9, v31
	v_add_f32_e32 v18, v18, v32
	v_exp_f32_e32 v8, v8
	v_cvt_i32_f32_e32 v19, v33
	v_exp_f32_e32 v18, v18
	s_mov_b32 s37, 0xc2ce8ed0
	v_ldexp_f32 v8, v8, v9
	v_cmp_ngt_f32_e32 vcc, s37, v6
	s_mov_b32 s38, 0x42b17218
	v_ldexp_f32 v9, v18, v19
	v_cndmask_b32_e32 v8, 0, v8, vcc
	v_cmp_ngt_f32_e32 vcc, s37, v3
	v_mov_b32_e32 v7, 0x7f800000
	s_ashr_i32 s9, s8, 31
	v_cndmask_b32_e32 v9, 0, v9, vcc
	v_cmp_nlt_f32_e32 vcc, s38, v6
	s_mov_b32 s10, 8
	s_lshl_b64 s[18:19], s[8:9], 12
	v_cndmask_b32_e32 v6, v7, v8, vcc
	v_cmp_nlt_f32_e32 vcc, s38, v3
	s_add_u32 s18, s4, s18
	s_addc_u32 s19, s5, s19
	v_cndmask_b32_e32 v3, v7, v9, vcc
	s_ashr_i32 s11, s10, 31
	v_sub_f32_e32 v3, v6, v3
	s_lshl_b64 s[22:23], s[8:9], 11
	s_lshl_b64 s[20:21], s[10:11], 12
	v_add_f32_e32 v6, 0x3e4ccccd, v3
	s_mov_b32 s34, 0x3f4ccccd
	s_brev_b32 s35, 48
	s_add_u32 s22, s4, s22
	v_mov_b32_e32 v8, v6
	s_mov_b64 s[12:13], 0xb000000
	s_mov_b64 s[14:15], 0xc000000
	s_mov_b64 s[16:17], 0x8000000
	s_brev_b32 s36, 16
	v_mov_b32_e32 v2, 0x358637bd
	s_addc_u32 s23, s5, s23
	s_lshl_b64 s[30:31], s[10:11], 11
	v_mov_b32_e32 v7, v6
	v_mov_b32_e32 v3, v6
	v_xor_b32_e32 v8, 0x80000000, v8
	s_mov_b32 s9, 0xf800000
	v_mov_b32_e32 v30, 0x260
	s_mov_b32 s11, 0xe000000
	s_waitcnt vmcnt(0)
	v_pk_mul_f32 v[10:11], v[10:11], s[34:35] op_sel_hi:[1,0]
	v_pk_mul_f32 v[12:13], v[12:13], s[34:35] op_sel_hi:[1,0]
	v_pk_mul_f32 v[14:15], v[14:15], s[34:35] op_sel_hi:[1,0]
	v_pk_mul_f32 v[16:17], v[16:17], s[34:35] op_sel_hi:[1,0]
	v_pk_mul_f32 v[18:19], v[22:23], s[34:35] op_sel_hi:[1,0]
	v_pk_mul_f32 v[20:21], v[20:21], s[34:35] op_sel_hi:[1,0]
	v_pk_mul_f32 v[22:23], v[24:25], s[34:35] op_sel_hi:[1,0]
	v_pk_mul_f32 v[24:25], v[26:27], s[34:35] op_sel_hi:[1,0]

.LBB0_566:
	s_cmp_gt_i32 s27, 5
	s_cselect_b64 s[4:5], -1, 0
	s_and_b64 s[6:7], s[6:7], s[4:5]
	s_andn2_b64 vcc, exec, s[6:7]
	s_cbranch_vccnz .LBB0_616
	s_waitcnt vmcnt(0)
	v_cmp_eq_u32_e32 vcc, 0, v0
	s_waitcnt vmcnt(0) lgkmcnt(0)
	s_barrier
	s_and_saveexec_b64 s[6:7], vcc
	s_cbranch_execz .LBB0_615
	s_and_b32 s8, s2, 7
	s_lshl_b32 s8, s8, 2
	s_bfe_u32 s9, s2, 0x20003
	s_add_i32 s8, s8, s9
	s_lshl_b32 s8, s8, 6
	s_add_i32 s8, s8, 0x6400
	v_mov_b32_e32 v1, s8
	s_mul_i32 s9, s33, s33
	s_lshl_b32 s9, s9, 16
	s_lshl_b32 s10, s33, 8
	s_or_b32 s9, s9, s10
	s_or_b32 s9, s9, 1
	v_mov_b32_e32 v2, s9
	global_atomic_add v1, v2, s[24:25]
	s_mov_b64 s[70:71], exec
	s_mov_b64 exec, -1
	s_load_dwordx2 s[90:91], s[0:1], 0x0
	s_and_b32 s80, s2, 7
	s_lshl_b32 s80, s80, 2
	s_bfe_u32 s81, s2, 0x20003
	s_add_i32 s80, s80, s81
	s_lshr_b32 s81, s2, 5
	s_lshl_b32 s80, s80, 21
	s_lshl_b32 s81, s81, 10
	s_add_u32 s80, s80, s81
	s_lshr_b32 s82, s28, 2
	s_lshl_b32 s82, s82, 19
	s_add_u32 s80, s80, s82
	s_and_b32 s82, s28, 3
	s_lshl_b32 s82, s82, 7
	s_add_u32 s80, s80, s82
	v_and_b32_e32 v202, 15, v0
	v_lshlrev_b32_e32 v202, 13, v202
	v_bfe_u32 v203, v0, 4, 2
	v_lshl_or_b32 v202, v203, 5, v202
	s_waitcnt lgkmcnt(0)
	s_add_u32 s90, s90, s80
	s_addc_u32 s91, s91, 0
	global_load_dwordx4 v[126:129], v202, s[90:91] nt
	global_load_dwordx4 v[122:125], v202, s[90:91] offset:16 nt
	global_load_dwordx4 v[118:121], v202, s[90:91] offset:512 nt
	global_load_dwordx4 v[114:117], v202, s[90:91] offset:528 nt
	s_add_u32 s90, s90, 0x20000
	s_addc_u32 s91, s91, 0
	global_load_dwordx4 v[110:113], v202, s[90:91] nt
	global_load_dwordx4 v[106:109], v202, s[90:91] offset:16 nt
	global_load_dwordx4 v[102:105], v202, s[90:91] offset:512 nt
	global_load_dwordx4 v[98:101], v202, s[90:91] offset:528 nt
	s_add_u32 s90, s90, 0x20000
	s_addc_u32 s91, s91, 0
	global_load_dwordx4 v[94:97], v202, s[90:91] nt
	global_load_dwordx4 v[90:93], v202, s[90:91] offset:16 nt
	global_load_dwordx4 v[86:89], v202, s[90:91] offset:512 nt
	global_load_dwordx4 v[154:157], v202, s[90:91] offset:528 nt
	s_add_u32 s90, s90, 0x20000
	s_addc_u32 s91, s91, 0
	global_load_dwordx4 v[82:85], v202, s[90:91] nt
	global_load_dwordx4 v[158:161], v202, s[90:91] offset:16 nt
	global_load_dwordx4 v[162:165], v202, s[90:91] offset:512 nt
	global_load_dwordx4 v[166:169], v202, s[90:91] offset:528 nt
	s_add_u32 s90, s90, 0xa0000
	s_addc_u32 s91, s91, 0
	global_load_dwordx4 v[170:173], v202, s[90:91] nt
	global_load_dwordx4 v[174:177], v202, s[90:91] offset:16 nt
	global_load_dwordx4 v[178:181], v202, s[90:91] offset:512 nt
	global_load_dwordx4 v[182:185], v202, s[90:91] offset:528 nt
	s_add_u32 s90, s90, 0x20000
	s_addc_u32 s91, s91, 0
	global_load_dwordx4 v[186:189], v202, s[90:91] nt
	global_load_dwordx4 v[190:193], v202, s[90:91] offset:16 nt
	global_load_dwordx4 v[194:197], v202, s[90:91] offset:512 nt
	global_load_dwordx4 v[198:201], v202, s[90:91] offset:528 nt
	s_add_u32 s90, s90, 0x20000
	s_addc_u32 s91, s91, 0
	global_load_dwordx4 v[206:209], v202, s[90:91] nt
	global_load_dwordx4 v[210:213], v202, s[90:91] offset:16 nt
	global_load_dwordx4 v[214:217], v202, s[90:91] offset:512 nt
	global_load_dwordx4 v[218:221], v202, s[90:91] offset:528 nt
	s_add_u32 s90, s90, 0x20000
	s_addc_u32 s91, s91, 0
	global_load_dwordx4 v[222:225], v202, s[90:91] nt
	global_load_dwordx4 v[226:229], v202, s[90:91] offset:16 nt
	global_load_dwordx4 v[230:233], v202, s[90:91] offset:512 nt
	global_load_dwordx4 v[234:237], v202, s[90:91] offset:528 nt
.Lxpre_skip_b:
	s_mov_b64 exec, s[70:71]
	v_mov_b32_e32 v3, 0x7600
	s_mov_b32 s14, 0
